# attention loop: one static s_setprio 1 for the younger half (waves 4-7), on top of v31
# speedup vs baseline: 1.0065x; 1.0016x over previous
; __device__ __forceinline__ int v_st(int k, int c) { const int kk = (k & ~0xC) | ((k & 4) << 1) | ((k & 8) >> 1); return ((kk >> 3) * 4 + (c >> 5)) * 512 + ((kk & 7) * 32 + (c & 31)) * 2; }
; __device__ __forceinline__ int v_rd_base(int lane) { return ((lane & 3) << 3) | (((lane >> 2) & 3) << 6) | (((lane >> 4) & 1) << 5) | (((lane >> 5) & 1) << 8); }
; #define SWAIT() asm volatile("s_waitcnt vmcnt(0)" ::: "memory")
; __device__ __forceinline__ void partialSM(f32x16& p0, f32x16& p1, float mnC) {
;     ...
;   for (int r = 0; r < 16; ++r) p0[r] = fmaf(p0[r], C, mnC);
; #pragma unroll
;   for (int r = 0; r < 16; ++r) p1[r] = fmaf(p1[r], C, mnC);
; #pragma unroll
;   for (int r = 0; r < 16; ++r) p0[r] = __builtin_amdgcn_exp2f(p0[r]);
; __device__ __forceinline__ void attn_dense_body(const bf16* __restrict__ Qb, const bf16* __restrict__ Kh, const bf16* __restrict__ Vh,
;                                                 bf16* __restrict__ Ob, int seq, char* lds, const int tid, const float mnC) {
;   const int wid = tid >> 6, lane = tid & 63, r32 = lane & 31, hi = lane >> 5;
;   bf16* V_lds = (bf16*)lds; bf16* K_lds = (bf16*)(lds + 2 * SHM_V);
;   float* ws = (float*)(lds + 2 * SHM_V + 2 * SHM_K) + wid * 64; float* li_l = ws;
;   float l_reg = 0; f32x16 o[4] = {}; bf16x8 qr[8];
;   const bf16* Qw = Qb + (long)(wid * QBLK + r32) * LDQ + hi * 8;
; #pragma unroll
;   for (int d0 = 0; d0 < 8; ++d0) qr[d0] = ld8(Qw + d0 * 16);
;   const int sr = tid >> 4, sc = (tid & 15) * 8, vst0 = v_st(sr, sc), vst1 = v_st(32 + sr, sc);
;   const int vb0 = (int)(uintptr_t)V_lds + v_rd_base(lane);
;   bf16x8 s0_vs0, s0_vs1, s0_ks0, s0_ks1;
;     ...
;   f32x16 pA0, pA1, pB0, pB1; bf16x8 pa0, pa1, pa2, pa3; const int NT = seq / KVBLK;
;   SLOAD0(0);
;   bf16x8 t1_vs0 = ld8(&Vh[(long)(KVBLK + sr) * LDK + sc]), t1_vs1 = ld8(&Vh[(long)(KVBLK + 32 + sr) * LDK + sc]);
;   bf16x8 t1_ks0 = ld8(&Kh[(long)(KVBLK + sr) * LDK + sc]), t1_ks1 = ld8(&Kh[(long)(KVBLK + 32 + sr) * LDK + sc]);
;   asm volatile("s_waitcnt vmcnt(4)" ::: "memory"); SWRITE0(0); __syncthreads();
;   qkt(pA0, pA1, K_lds, qr, r32, hi); partialSM(pA0, pA1, mnC);
;   s0_vs0 = t1_vs0; s0_vs1 = t1_vs1; s0_ks0 = t1_ks0; s0_ks1 = t1_ks1;
;   SWAIT(); SWRITE0(1); __syncthreads();
;   if (__builtin_amdgcn_readfirstlane(wid) >= 4) __builtin_amdgcn_s_setprio(1);
.LBB0_1039:
	s_lshr_b32 s12, s8, 2
	v_and_b32_e32 v159, 63, v174
	s_and_b32 s12, s12, 1
	s_and_b32 s13, s4, 3
	v_mov_b32_e32 v153, v152
	s_nop 5
	v_pk_fma_f32 v[168:169], v[0:1], s[26:27], v[156:157] op_sel_hi:[1,0,1]
	s_mul_i32 s12, s12, 0x840000
	s_lshl_b32 s13, s13, 8
	v_lshlrev_b32_e32 v1, 4, v159
	v_pk_fma_f32 v[166:167], v[2:3], s[26:27], v[152:153] op_sel_hi:[1,0,1]
	s_or_b32 s13, s13, s12
	v_lshlrev_b32_e32 v0, 3, v159
	v_and_b32_e32 v1, 0xc0, v1
	v_lshlrev_b32_e32 v2, 1, v159
	v_and_or_b32 v1, v0, 24, v1
	v_and_b32_e32 v2, 32, v2
	v_and_b32_e32 v0, 0x100, v0
	s_cmp_lg_u32 0, -1
	v_or3_b32 v0, v1, v2, v0
	s_cselect_b32 s14, 0, 0
	v_fmamk_f32 v16, v16, 0x3f800000, v152
	v_fmamk_f32 v17, v17, 0x3f800000, v152
	v_fmamk_f32 v18, v18, 0x3f800000, v152
	v_fmamk_f32 v19, v19, 0x3f800000, v152
	v_fmamk_f32 v20, v20, 0x3f800000, v152
	v_fmamk_f32 v21, v21, 0x3f800000, v152
	v_fmamk_f32 v22, v22, 0x3f800000, v152
	v_fmamk_f32 v23, v23, 0x3f800000, v152
	v_fmamk_f32 v24, v24, 0x3f800000, v152
	v_fmamk_f32 v25, v25, 0x3f800000, v152
	v_fmamk_f32 v26, v26, 0x3f800000, v152
	v_fmamk_f32 v27, v27, 0x3f800000, v152
	v_fmamk_f32 v28, v28, 0x3f800000, v152
	v_fmamk_f32 v29, v29, 0x3f800000, v152
	v_fmamk_f32 v30, v30, 0x3f800000, v152
	v_fmamk_f32 v31, v31, 0x3f800000, v152
	v_add_u32_e32 v173, s14, v0
	s_addk_i32 s14, 0x4000
	v_pk_fma_f32 v[144:145], v[14:15], s[26:27], v[152:153] op_sel_hi:[1,0,1]
	v_pk_fma_f32 v[146:147], v[12:13], s[26:27], v[152:153] op_sel_hi:[1,0,1]
	v_pk_fma_f32 v[148:149], v[10:11], s[26:27], v[152:153] op_sel_hi:[1,0,1]
	v_pk_fma_f32 v[162:163], v[8:9], s[26:27], v[152:153] op_sel_hi:[1,0,1]
	v_pk_fma_f32 v[150:151], v[6:7], s[26:27], v[152:153] op_sel_hi:[1,0,1]
	v_pk_fma_f32 v[164:165], v[4:5], s[26:27], v[152:153] op_sel_hi:[1,0,1]
	v_exp_f32_e32 v199, v16
	v_exp_f32_e32 v201, v17
	v_exp_f32_e32 v198, v18
	v_exp_f32_e32 v203, v19
	v_exp_f32_e32 v200, v20
	v_exp_f32_e32 v202, v21
	v_exp_f32_e32 v196, v22
	v_exp_f32_e32 v197, v23
	v_exp_f32_e32 v193, v24
	v_exp_f32_e32 v195, v25
	v_exp_f32_e32 v192, v26
	v_exp_f32_e32 v194, v27
	v_exp_f32_e32 v189, v28
	v_exp_f32_e32 v191, v29
	v_exp_f32_e32 v188, v30
	v_exp_f32_e32 v190, v31
	v_add_u32_e32 v153, s14, v0
	v_and_b32_e32 v0, 15, v174
	s_add_u32 s14, s2, s13
	v_lshl_or_b32 v32, v0, 4, v32
	s_addc_u32 s15, s3, 0
	v_lshl_add_u64 v[0:1], s[14:15], 0, v[32:33]
	s_mov_b64 s[14:15], 0xeb38000
	v_mov_b32_e32 v187, 0
	s_mov_b32 s12, -1
	v_lshl_add_u64 v[160:161], v[0:1], 0, s[14:15]
	v_mov_b32_e32 v0, 0
	v_mov_b32_e32 v1, v187
	v_mov_b32_e32 v2, v187
	v_mov_b32_e32 v3, v187
	v_mov_b32_e32 v4, v187
	v_mov_b32_e32 v5, v187
	v_mov_b32_e32 v6, v187
	v_mov_b32_e32 v7, v187
	v_mov_b32_e32 v8, v187
	v_mov_b32_e32 v9, v187
	v_mov_b32_e32 v10, v187
	v_mov_b32_e32 v11, v187
	v_mov_b32_e32 v12, v187
	v_mov_b32_e32 v13, v187
	v_mov_b32_e32 v14, v187
	v_mov_b32_e32 v15, v187
	v_mov_b32_e32 v16, 0
	v_mov_b32_e32 v17, v187
	v_mov_b32_e32 v18, v187
	v_mov_b32_e32 v19, v187
	v_mov_b32_e32 v20, v187
	v_mov_b32_e32 v21, v187
	v_mov_b32_e32 v22, v187
	v_mov_b32_e32 v23, v187
	v_mov_b32_e32 v24, v187
	v_mov_b32_e32 v25, v187
	v_mov_b32_e32 v26, v187
	v_mov_b32_e32 v27, v187
	v_mov_b32_e32 v28, v187
	v_mov_b32_e32 v29, v187
	v_mov_b32_e32 v30, v187
	v_mov_b32_e32 v31, v187
	v_mov_b32_e32 v32, 0
	v_mov_b32_e32 v33, v187
	v_mov_b32_e32 v34, v187
	v_mov_b32_e32 v35, v187
	v_mov_b32_e32 v36, v187
	v_mov_b32_e32 v37, v187
	v_mov_b32_e32 v38, v187
	v_mov_b32_e32 v39, v187
	v_mov_b32_e32 v40, v187
	v_mov_b32_e32 v41, v187
	v_mov_b32_e32 v42, v187
	v_mov_b32_e32 v43, v187
	v_mov_b32_e32 v44, v187
	v_mov_b32_e32 v45, v187
	v_mov_b32_e32 v46, v187
	v_mov_b32_e32 v47, v187
	v_mov_b32_e32 v48, 0
	v_mov_b32_e32 v49, v187
	v_mov_b32_e32 v50, v187
	v_mov_b32_e32 v51, v187
	v_mov_b32_e32 v52, v187
	v_mov_b32_e32 v53, v187
	v_mov_b32_e32 v54, v187
	v_mov_b32_e32 v55, v187
	v_mov_b32_e32 v56, v187
	v_mov_b32_e32 v57, v187
	v_mov_b32_e32 v58, v187
	v_mov_b32_e32 v59, v187
	v_mov_b32_e32 v60, v187
	v_mov_b32_e32 v61, v187
	v_mov_b32_e32 v62, v187
	v_mov_b32_e32 v63, v187
	v_lshrrev_b32_e32 v216, 6, v174
	v_lshrrev_b32_e32 v217, 4, v159
	v_and_b32_e32 v218, 15, v159
	v_readfirstlane_b32 s98, v216
	v_xor_b32_e32 v218, v218, v217
	v_and_b32_e32 v219, 1, v216
	v_lshlrev_b32_e32 v219, 3, v219
	v_xor_b32_e32 v218, v218, v219
	v_lshlrev_b32_e32 v218, 4, v218
	v_lshl_or_b32 v218, v217, 10, v218
	v_lshl_or_b32 v216, v216, 13, v218
	v_xor_b32_e32 v217, 64, v216
	v_add_u32_e32 v217, 0x1000, v217
	s_and_b32 s99, s98, 1
	s_lshl_b32 s99, s99, 2
	s_lshr_b32 s100, s98, 1
	s_lshl_b32 s100, s100, 4
	s_or_b32 s99, s99, s100
	s_lshl_b32 s99, s99, 10
	v_bfe_u32 v218, v159, 2, 2
	v_bfe_u32 v219, v159, 4, 1
	v_lshl_or_b32 v218, v219, 3, v218
	v_lshlrev_b32_e32 v218, 10, v218
	v_lshrrev_b32_e32 v219, 5, v159
	v_lshl_or_b32 v218, v219, 6, v218
	v_and_b32_e32 v219, 3, v159
	v_lshl_or_b32 v218, v219, 4, v218
	v_add_u32_e32 v218, s99, v218
	v_add_u32_e32 v219, 0x80, v218
	s_lshl_b32 s98, s98, 11
	s_bfe_u32 s100, s8, 0x10002
	s_mul_i32 s100, s100, 0x840000
	s_and_b32 s101, s8, 3
	s_lshl_b32 s101, s101, 8
	s_add_u32 s100, s100, s101
	s_add_u32 s14, s2, s100
	s_addc_u32 s15, s3, 0
	s_add_u32 s16, s14, 0xeb10000
	s_addc_u32 s17, s15, 0
	s_add_u32 s14, s14, 0xda20000
	s_addc_u32 s15, s15, 0
	v_mov_b32_e32 v136, 0
	v_mov_b32_e32 v137, 0
	v_mov_b32_e32 v138, 0
	v_mov_b32_e32 v139, 0
	v_mov_b32_e32 v140, 0
	v_mov_b32_e32 v141, 0
	v_mov_b32_e32 v142, 0
	v_mov_b32_e32 v143, 0
	v_mov_b32_e32 v208, 0
	v_mov_b32_e32 v209, 0
	v_mov_b32_e32 v210, 0
	v_mov_b32_e32 v211, 0
	v_mov_b32_e32 v228, 0
	v_mov_b32_e32 v229, 0
	v_mov_b32_e32 v230, 0
	v_mov_b32_e32 v231, 0
	v_mov_b32_e32 v232, 0
	v_mov_b32_e32 v233, 0
	v_mov_b32_e32 v234, 0
	v_mov_b32_e32 v235, 0
	v_mov_b32_e32 v236, 0
	v_mov_b32_e32 v237, 0
	v_mov_b32_e32 v238, 0
	v_mov_b32_e32 v239, 0
	v_mov_b32_e32 v240, 0
	v_mov_b32_e32 v241, 0
	v_mov_b32_e32 v242, 0
	v_mov_b32_e32 v243, 0
	v_mov_b32_e32 v204, 0
	v_mov_b32_e32 v205, 0
	v_mov_b32_e32 v206, 0
	v_mov_b32_e32 v207, 0
	v_exp_f32_e32 v168, v168
	v_exp_f32_e32 v169, v169
	v_exp_f32_e32 v166, v166
	v_exp_f32_e32 v167, v167
	v_exp_f32_e32 v164, v164
	v_exp_f32_e32 v165, v165
	v_exp_f32_e32 v150, v150
	v_exp_f32_e32 v151, v151
	v_exp_f32_e32 v162, v162
	v_exp_f32_e32 v163, v163
	v_exp_f32_e32 v148, v148
	v_exp_f32_e32 v149, v149
	v_exp_f32_e32 v146, v146
	v_exp_f32_e32 v147, v147
	v_exp_f32_e32 v144, v144
	v_exp_f32_e32 v145, v145
	v_add_u32_e32 v153, 0x10000, v173
	s_add_i32 m0, s98, 0x10000
	s_nop 0
	global_load_lds_dwordx4 v218, s[16:17]
	s_add_i32 m0, s98, 0x10400
	s_nop 0
	global_load_lds_dwordx4 v219, s[16:17]
	s_add_i32 m0, s98, 0x4000
	s_nop 0
	global_load_lds_dwordx4 v216, s[14:15]
	s_add_i32 m0, s98, 0x4400
	s_nop 0
	global_load_lds_dwordx4 v217, s[14:15]
	s_add_u32 s14, s14, 0x10000
	s_addc_u32 s15, s15, 0
	s_add_u32 s16, s16, 0x10000
	s_addc_u32 s17, s17, 0
	s_bitcmp1_b32 s98, 13
	s_cbranch_scc0 .Lattn_prio_skip
	s_setprio 1
.Lattn_prio_skip:
	s_mov_b32 s12, 43
